# v41 plus attention-A epilogue gate loads issued up front (8 loads, counted vmcnt)
# speedup vs baseline: 1.0140x; 1.0029x over previous
; __device__ __forceinline__ int crow(int r, int hi) { return (r & 3) + 8 * (r >> 2) + 4 * hi; }
;   __device__ __forceinline__ void operator()(f32x16 (&o)[4], const float (&rli)[16], int wid, int r32, int hi, int lane, char* lds) const {
;     ...
;     unsigned wb = (unsigned)(4 * hi * 128 + r32); asm volatile("" : "+v"(wb));
; #pragma unroll
;     for (int r = 0; r < 16; ++r) { const unsigned cr = (r & 3) + 8 * (r >> 2);
; #pragma unroll
;       for (int d0 = 0; d0 < 4; ++d0) st[wb + cr * 128 + d0 * 32] = o[d0][r] * rli[r]; }
;     unsigned rr = (unsigned)(lane >> 4), c8 = (unsigned)(lane & 15) * 8; asm volatile("" : "+v"(rr), "+v"(c8));
;     const unsigned zb = (unsigned)(wid * QBLK + rr) * A_IN + c8, ob = (unsigned)(wid * QBLK + rr) * DM + c8, sb = rr * 128 + c8;
; #pragma unroll
;     for (int i = 0; i < 8; ++i) {
;       const f32x4 a = *(const f32x4*)(st + sb + i * 512), b = *(const f32x4*)(st + sb + i * 512 + 4);
;       const bf16x8 zz = *(const bf16x8*)(z0 + zb + (unsigned)(i * 4) * A_IN);
; template <int LD, class Epi> ...
;     ...
;   if (hie == 0) li_l[r32e] = lsum; asm volatile("s_waitcnt lgkmcnt(0)" ::: "memory");
;   float rli[16];
; #pragma unroll
;   for (int r = 0; r < 16; ++r) rli[r] = __builtin_amdgcn_rcpf(li_l[crow(r, hie)]);
.LBB0_37:
	s_or_b64 exec, exec, s[12:13]
	v_ashrrev_i32_e32 v74, 5, v64
	s_waitcnt lgkmcnt(0)
	v_lshl_add_u32 v75, v74, 4, s20
	ds_read_b128 v[66:69], v75
	ds_read_b128 v[70:73], v75 offset:32
	v_lshl_or_b32 v65, v74, 9, v65
	s_lshl_b64 s[10:11], s[10:11], 11
	s_add_u32 s10, s70, s10
	s_waitcnt lgkmcnt(0)
	v_rcp_f32_e32 v76, v66
	v_rcp_f32_e32 v77, v67
	v_rcp_f32_e32 v78, v68
	v_rcp_f32_e32 v79, v69
	v_rcp_f32_e32 v80, v70
	ds_read_b128 v[66:69], v75 offset:64
	v_rcp_f32_e32 v81, v71
	v_rcp_f32_e32 v82, v72
	v_rcp_f32_e32 v83, v73
	ds_read_b128 v[70:73], v75 offset:96
	v_mul_f32_e32 v0, v0, v76
	v_lshl_add_u32 v65, v65, 2, s21
	v_mul_f32_e32 v16, v16, v76
	ds_write2_b32 v65, v0, v16 offset1:32
	v_mul_f32_e32 v0, v32, v76
	v_mul_f32_e32 v16, v48, v76
	ds_write2_b32 v65, v0, v16 offset0:64 offset1:96
	v_mul_f32_e32 v0, v1, v77
	v_mul_f32_e32 v1, v17, v77
	ds_write2_b32 v65, v0, v1 offset0:128 offset1:160
	v_mul_f32_e32 v0, v33, v77
	v_mul_f32_e32 v1, v49, v77
	ds_write2_b32 v65, v0, v1 offset0:192 offset1:224
	v_mul_f32_e32 v0, v2, v78
	v_mul_f32_e32 v1, v18, v78
	v_add_u32_e32 v2, 0x400, v65
	ds_write2_b32 v2, v0, v1 offset1:32
	v_mul_f32_e32 v0, v34, v78
	v_mul_f32_e32 v1, v50, v78
	ds_write2_b32 v2, v0, v1 offset0:64 offset1:96
	v_mul_f32_e32 v0, v3, v79
	v_mul_f32_e32 v1, v19, v79
	ds_write2_b32 v2, v0, v1 offset0:128 offset1:160
	v_mul_f32_e32 v0, v35, v79
	v_mul_f32_e32 v1, v51, v79
	ds_write2_b32 v2, v0, v1 offset0:192 offset1:224
	v_mul_f32_e32 v0, v4, v80
	v_mul_f32_e32 v1, v20, v80
	v_add_u32_e32 v2, 0x1000, v65
	ds_write2_b32 v2, v0, v1 offset1:32
	v_mul_f32_e32 v0, v36, v80
	v_mul_f32_e32 v1, v52, v80
	ds_write2_b32 v2, v0, v1 offset0:64 offset1:96
	v_mul_f32_e32 v0, v5, v81
	v_mul_f32_e32 v1, v21, v81
	ds_write2_b32 v2, v0, v1 offset0:128 offset1:160
	v_mul_f32_e32 v0, v37, v81
	v_mul_f32_e32 v1, v53, v81
	s_waitcnt lgkmcnt(0)
	v_rcp_f32_e32 v66, v66
	ds_write2_b32 v2, v0, v1 offset0:192 offset1:224
	v_mul_f32_e32 v0, v6, v82
	v_mul_f32_e32 v1, v22, v82
	v_add_u32_e32 v2, 0x1400, v65
	ds_write2_b32 v2, v0, v1 offset1:32
	v_mul_f32_e32 v0, v38, v82
	v_mul_f32_e32 v1, v54, v82
	v_rcp_f32_e32 v67, v67
	ds_write2_b32 v2, v0, v1 offset0:64 offset1:96
	v_mul_f32_e32 v0, v7, v83
	v_mul_f32_e32 v1, v23, v83
	ds_write2_b32 v2, v0, v1 offset0:128 offset1:160
	v_mul_f32_e32 v0, v39, v83
	v_mul_f32_e32 v1, v55, v83
	v_rcp_f32_e32 v68, v68
	ds_write2_b32 v2, v0, v1 offset0:192 offset1:224
	v_mul_f32_e32 v0, v8, v66
	v_mul_f32_e32 v1, v24, v66
	v_add_u32_e32 v2, 0x2000, v65
	ds_write2_b32 v2, v0, v1 offset1:32
	v_mul_f32_e32 v0, v40, v66
	v_mul_f32_e32 v1, v56, v66
	v_rcp_f32_e32 v69, v69
	ds_write2_b32 v2, v0, v1 offset0:64 offset1:96
	v_mul_f32_e32 v0, v9, v67
	v_mul_f32_e32 v1, v25, v67
	ds_write2_b32 v2, v0, v1 offset0:128 offset1:160
	v_mul_f32_e32 v0, v41, v67
	v_mul_f32_e32 v1, v57, v67
	v_rcp_f32_e32 v70, v70
	ds_write2_b32 v2, v0, v1 offset0:192 offset1:224
	v_mul_f32_e32 v0, v10, v68
	v_mul_f32_e32 v1, v26, v68
	v_add_u32_e32 v2, 0x2400, v65
	ds_write2_b32 v2, v0, v1 offset1:32
	v_mul_f32_e32 v0, v42, v68
	v_mul_f32_e32 v1, v58, v68
	v_rcp_f32_e32 v71, v71
	ds_write2_b32 v2, v0, v1 offset0:64 offset1:96
	v_mul_f32_e32 v0, v11, v69
	v_mul_f32_e32 v1, v27, v69
	ds_write2_b32 v2, v0, v1 offset0:128 offset1:160
	v_mul_f32_e32 v0, v43, v69
	v_mul_f32_e32 v1, v59, v69
	v_rcp_f32_e32 v72, v72
	ds_write2_b32 v2, v0, v1 offset0:192 offset1:224
	v_mul_f32_e32 v0, v12, v70
	v_mul_f32_e32 v1, v28, v70
	v_add_u32_e32 v2, 0x3000, v65
	ds_write2_b32 v2, v0, v1 offset1:32
	v_mul_f32_e32 v0, v44, v70
	v_mul_f32_e32 v1, v60, v70
	v_rcp_f32_e32 v73, v73
	ds_write2_b32 v2, v0, v1 offset0:64 offset1:96
	v_mul_f32_e32 v0, v13, v71
	v_mul_f32_e32 v1, v29, v71
	ds_write2_b32 v2, v0, v1 offset0:128 offset1:160
	v_mul_f32_e32 v0, v45, v71
	v_mul_f32_e32 v1, v61, v71
	ds_write2_b32 v2, v0, v1 offset0:192 offset1:224
	v_mul_f32_e32 v0, v14, v72
	v_mul_f32_e32 v1, v30, v72
	v_add_u32_e32 v2, 0x3400, v65
	ds_write2_b32 v2, v0, v1 offset1:32
	v_mul_f32_e32 v0, v46, v72
	v_mul_f32_e32 v1, v62, v72
	ds_write2_b32 v2, v0, v1 offset0:64 offset1:96
	v_mul_f32_e32 v0, v15, v73
	v_mul_f32_e32 v1, v31, v73
	ds_write2_b32 v2, v0, v1 offset0:128 offset1:160
	v_mul_f32_e32 v0, v47, v73
	v_mul_f32_e32 v1, v63, v73
	ds_write2_b32 v2, v0, v1 offset0:192 offset1:224
	v_lshlrev_b32_e32 v0, 3, v64
	v_ashrrev_i32_e32 v1, 4, v64
	v_and_b32_e32 v0, 0x78, v0
	s_addc_u32 s11, s71, s11
	v_add_u32_e32 v4, s18, v1
	v_mad_u64_u32 v[2:3], s[12:13], v4, s61, v[0:1]
	s_add_u32 s8, s36, s8
	s_movk_i32 s12, 0xf400
	s_addc_u32 s9, s37, s9
	v_mad_u64_u32 v[16:17], s[12:13], v4, s12, v[2:3]
	v_mov_b32_e32 v3, v161
	v_lshl_add_u64 v[2:3], v[2:3], 1, s[8:9]
	v_add_co_u32_e32 v4, vcc, s56, v2
	v_lshlrev_b32_e32 v1, 9, v1
	s_nop 0
	v_addc_co_u32_e32 v5, vcc, 0, v3, vcc
	global_load_dwordx4 v[40:43], v[4:5], off offset:2048
	v_mov_b32_e32 v32, 0xa000
	v_mov_b32_e32 v33, 0
	v_lshl_add_u64 v[34:35], v[4:5], 0, v[32:33]
	global_load_dwordx4 v[44:47], v[34:35], off offset:2048
	v_lshl_add_u64 v[34:35], v[34:35], 0, v[32:33]
	global_load_dwordx4 v[48:51], v[34:35], off offset:2048
	v_lshl_add_u64 v[34:35], v[34:35], 0, v[32:33]
	global_load_dwordx4 v[52:55], v[34:35], off offset:2048
	v_lshl_add_u64 v[34:35], v[34:35], 0, v[32:33]
	global_load_dwordx4 v[56:59], v[34:35], off offset:2048
	v_lshl_add_u64 v[34:35], v[34:35], 0, v[32:33]
	global_load_dwordx4 v[60:63], v[34:35], off offset:2048
	v_lshl_add_u64 v[34:35], v[34:35], 0, v[32:33]
	global_load_dwordx4 v[64:67], v[34:35], off offset:2048
	v_lshl_add_u64 v[34:35], v[34:35], 0, v[32:33]
	global_load_dwordx4 v[68:71], v[34:35], off offset:2048
	v_lshlrev_b32_e32 v0, 2, v0
	s_add_u32 s4, s10, s4
	s_addc_u32 s5, s11, s5
	s_mov_b32 s8, 0xb000
	s_add_i32 s35, s35, 1
	s_cmp_eq_u32 s35, 12
	s_waitcnt vmcnt(7)
; __device__ __forceinline__ unsigned pk4_fp8(float a, float b, float c, float d) { int p = __builtin_amdgcn_cvt_pk_fp8_f32(a, b, 0, false); return (unsigned)__builtin_amdgcn_cvt_pk_fp8_f32(c, d, p, true); }
; __device__ __forceinline__ float bf2f(bf16_t b) { return __uint_as_float((unsigned)b << 16); }
; __device__ __forceinline__ float silu_f(float z) { return z * __builtin_amdgcn_rcpf(1.f + __builtin_amdgcn_exp2f(-1.4426950408889634f * z)); }
;   __device__ __forceinline__ void operator()(f32x16 (&o)[4], const float (&rli)[16], int wid, int r32, int hi, int lane, char* lds) const {
;     ...
;     for (int i = 0; i < 8; ++i) {
;       const f32x4 a = *(const f32x4*)(st + sb + i * 512), b = *(const f32x4*)(st + sb + i * 512 + 4);
;       const bf16x8 zz = *(const bf16x8*)(z0 + zb + (unsigned)(i * 4) * A_IN);
;       float g[8];
; #pragma unroll
;       for (int k = 0; k < 8; ++k) g[k] = silu_f(bf2f((bf16_t)zz[k])) * F8_ASCALE;
;       u32x2 w; w.x = pk4_fp8(a[0] * g[0], a[1] * g[1], a[2] * g[2], a[3] * g[3]); w.y = pk4_fp8(b[0] * g[4], b[1] * g[5], b[2] * g[6], b[3] * g[7]);
;       *(u32x2*)(ao0 + ob + (unsigned)(i * 4) * DM) = w; }
	v_lshlrev_b32_e32 v17, 16, v40
	v_mul_f32_e32 v8, 0xbfb8aa3b, v17
	v_and_b32_e32 v18, 0xffff0000, v40
	v_exp_f32_e32 v8, v8
	v_mul_f32_e32 v4, 0xbfb8aa3b, v18
	v_exp_f32_e32 v9, v4
	v_add3_u32 v4, s21, v1, v0
	v_add_f32_e32 v0, 1.0, v8
	v_rcp_f32_e32 v0, v0
	v_add_f32_e32 v1, 1.0, v9
	v_rcp_f32_e32 v1, v1
	v_lshlrev_b32_e32 v20, 16, v42
	v_mul_f32_e32 v0, v0, v17
	v_lshlrev_b32_e32 v17, 16, v41
	v_mul_f32_e32 v1, v1, v18
	v_mul_f32_e32 v18, 0xbfb8aa3b, v17
	v_and_b32_e32 v5, 0xffff0000, v41
	v_exp_f32_e32 v18, v18
	v_mul_f32_e32 v19, 0xbfb8aa3b, v5
	v_exp_f32_e32 v19, v19
	v_mul_f32_e32 v21, 0xbfb8aa3b, v20
	v_add_f32_e32 v18, 1.0, v18
	v_rcp_f32_e32 v18, v18
	v_add_f32_e32 v19, 1.0, v19
	v_exp_f32_e32 v21, v21
	v_rcp_f32_e32 v19, v19
	v_mul_f32_e32 v17, v18, v17
	v_and_b32_e32 v6, 0xffff0000, v42
	v_add_f32_e32 v18, 1.0, v21
	v_mul_f32_e32 v5, v19, v5
	v_rcp_f32_e32 v18, v18
	v_mul_f32_e32 v19, 0xbfb8aa3b, v6
	v_exp_f32_e32 v19, v19
	ds_read_b128 v[8:11], v4
	ds_read_b128 v[12:15], v4 offset:16
	v_mul_f32_e32 v18, v18, v20
	v_lshlrev_b32_e32 v20, 16, v43
	v_and_b32_e32 v7, 0xffff0000, v43
	v_add_f32_e32 v19, 1.0, v19
	v_mul_f32_e32 v21, 0xbfb8aa3b, v20
	v_mul_f32_e32 v22, 0xbfb8aa3b, v7
	v_rcp_f32_e32 v19, v19
	v_exp_f32_e32 v21, v21
	v_exp_f32_e32 v22, v22
	v_mul_f32_e32 v0, 0x42800000, v0
	v_mul_f32_e32 v6, v19, v6
	v_add_f32_e32 v19, 1.0, v21
	v_add_f32_e32 v21, 1.0, v22
	v_mul_f32_e32 v1, 0x42800000, v1
	v_rcp_f32_e32 v19, v19
	v_rcp_f32_e32 v21, v21
	v_mul_f32_e32 v18, 0x42800000, v18
	v_mul_f32_e32 v6, 0x42800000, v6
	s_waitcnt lgkmcnt(1)
	v_mul_f32_e32 v8, v8, v0
	v_mul_f32_e32 v1, v9, v1
	v_mov_b32_e32 v0, v161
	v_cvt_pk_fp8_f32 v0, v8, v1
	s_waitcnt lgkmcnt(0)
	v_mul_f32_e32 v8, v12, v18
	v_mul_f32_e32 v6, v13, v6
	v_mov_b32_e32 v1, v161
	v_cvt_pk_fp8_f32 v1, v8, v6
	v_mul_f32_e32 v17, 0x42800000, v17
	v_mul_f32_e32 v5, 0x42800000, v5
	v_mul_f32_e32 v19, v19, v20
	v_mul_f32_e32 v7, v21, v7
	v_mul_f32_e32 v19, 0x42800000, v19
	v_mul_f32_e32 v7, 0x42800000, v7
	v_mul_f32_e32 v9, v10, v17
	v_mul_f32_e32 v5, v11, v5
	v_cvt_pk_fp8_f32 v0, v9, v5 op_sel:[0,0,1]
	v_mul_f32_e32 v5, v14, v19
	v_mul_f32_e32 v6, v15, v7
	v_cvt_pk_fp8_f32 v1, v5, v6 op_sel:[0,0,1]
	v_mov_b32_e32 v17, v161
	global_store_dwordx2 v16, v[0:1], s[4:5]
	v_add_co_u32_e32 v0, vcc, s8, v2
	s_nop 1
	v_addc_co_u32_e32 v1, vcc, 0, v3, vcc
	s_waitcnt vmcnt(7)
	v_lshlrev_b32_e32 v5, 16, v44
	v_mul_f32_e32 v0, 0xbfb8aa3b, v5
	v_and_b32_e32 v6, 0xffff0000, v44
	v_exp_f32_e32 v10, v0
	v_mul_f32_e32 v0, 0xbfb8aa3b, v6
	v_exp_f32_e32 v11, v0
	v_lshlrev_b32_e32 v21, 16, v46
	v_add_f32_e32 v10, 1.0, v10
	v_rcp_f32_e32 v18, v10
	v_add_f32_e32 v10, 1.0, v11
	v_rcp_f32_e32 v19, v10
	v_mul_f32_e32 v22, 0xbfb8aa3b, v21
	v_mul_f32_e32 v5, v18, v5
	v_lshlrev_b32_e32 v18, 16, v45
	v_mul_f32_e32 v6, v19, v6
	v_mul_f32_e32 v19, 0xbfb8aa3b, v18
	v_and_b32_e32 v7, 0xffff0000, v45
	v_exp_f32_e32 v19, v19
	v_mul_f32_e32 v20, 0xbfb8aa3b, v7
	v_exp_f32_e32 v20, v20
	v_exp_f32_e32 v22, v22
	v_add_f32_e32 v19, 1.0, v19
	v_rcp_f32_e32 v19, v19
	v_add_f32_e32 v20, 1.0, v20
	v_rcp_f32_e32 v20, v20
	v_and_b32_e32 v8, 0xffff0000, v46
	v_mul_f32_e32 v18, v19, v18
	v_add_f32_e32 v19, 1.0, v22
	v_mul_f32_e32 v7, v20, v7
	v_rcp_f32_e32 v19, v19
	v_mul_f32_e32 v20, 0xbfb8aa3b, v8
	v_exp_f32_e32 v20, v20
	v_lshl_add_u64 v[0:1], s[4:5], 0, v[16:17]
	v_mul_f32_e32 v19, v19, v21
	v_lshlrev_b32_e32 v21, 16, v47
	v_and_b32_e32 v9, 0xffff0000, v47
	v_add_f32_e32 v20, 1.0, v20
	v_mul_f32_e32 v22, 0xbfb8aa3b, v21
	v_mul_f32_e32 v23, 0xbfb8aa3b, v9
	v_rcp_f32_e32 v20, v20
	v_exp_f32_e32 v22, v22
	v_exp_f32_e32 v23, v23
	ds_read_b128 v[10:13], v4 offset:2048
	ds_read_b128 v[14:17], v4 offset:2064
	v_mul_f32_e32 v8, v20, v8
	v_add_f32_e32 v20, 1.0, v22
	v_add_f32_e32 v22, 1.0, v23
	v_mul_f32_e32 v5, 0x42800000, v5
	v_mul_f32_e32 v6, 0x42800000, v6
	v_rcp_f32_e32 v20, v20
	v_rcp_f32_e32 v22, v22
	v_mul_f32_e32 v18, 0x42800000, v18
	v_mul_f32_e32 v7, 0x42800000, v7
	v_mul_f32_e32 v19, 0x42800000, v19
	v_mul_f32_e32 v8, 0x42800000, v8
	s_waitcnt lgkmcnt(1)
	v_mul_f32_e32 v5, v10, v5
	v_mul_f32_e32 v10, v11, v6
	v_mov_b32_e32 v6, v161
	v_mul_f32_e32 v11, v12, v18
	v_mul_f32_e32 v12, v13, v7
	v_cvt_pk_fp8_f32 v6, v5, v10
	s_waitcnt lgkmcnt(0)
	v_mul_f32_e32 v5, v14, v19
	v_mul_f32_e32 v8, v15, v8
	v_mov_b32_e32 v7, v161
	v_cvt_pk_fp8_f32 v7, v5, v8
	v_mul_f32_e32 v20, v20, v21
	v_mul_f32_e32 v9, v22, v9
	v_mul_f32_e32 v20, 0x42800000, v20
	v_mul_f32_e32 v9, 0x42800000, v9
	v_mul_f32_e32 v5, v16, v20
	v_mul_f32_e32 v8, v17, v9
	v_cvt_pk_fp8_f32 v6, v11, v12 op_sel:[0,0,1]
	v_cvt_pk_fp8_f32 v7, v5, v8 op_sel:[0,0,1]
	s_movk_i32 s4, 0x2000
	v_add_co_u32_e32 v8, vcc, s4, v0
	s_mov_b32 s4, 0x15000
	s_nop 0
	v_addc_co_u32_e32 v9, vcc, 0, v1, vcc
	global_store_dwordx2 v[8:9], v[6:7], off
	v_add_co_u32_e32 v6, vcc, s4, v2
	s_mov_b32 s4, 0x1f000
	s_nop 0
	v_addc_co_u32_e32 v7, vcc, 0, v3, vcc
	s_waitcnt vmcnt(7)
; __device__ __forceinline__ unsigned pk4_fp8(float a, float b, float c, float d) { int p = __builtin_amdgcn_cvt_pk_fp8_f32(a, b, 0, false); return (unsigned)__builtin_amdgcn_cvt_pk_fp8_f32(c, d, p, true); }
; __device__ __forceinline__ float bf2f(bf16_t b) { return __uint_as_float((unsigned)b << 16); }
; __device__ __forceinline__ float silu_f(float z) { return z * __builtin_amdgcn_rcpf(1.f + __builtin_amdgcn_exp2f(-1.4426950408889634f * z)); }
;   __device__ __forceinline__ void operator()(f32x16 (&o)[4], const float (&rli)[16], int wid, int r32, int hi, int lane, char* lds) const {
;     ...
;     for (int i = 0; i < 8; ++i) {
;       const f32x4 a = *(const f32x4*)(st + sb + i * 512), b = *(const f32x4*)(st + sb + i * 512 + 4);
;       const bf16x8 zz = *(const bf16x8*)(z0 + zb + (unsigned)(i * 4) * A_IN);
;       float g[8];
; #pragma unroll
;       for (int k = 0; k < 8; ++k) g[k] = silu_f(bf2f((bf16_t)zz[k])) * F8_ASCALE;
;       u32x2 w; w.x = pk4_fp8(a[0] * g[0], a[1] * g[1], a[2] * g[2], a[3] * g[3]); w.y = pk4_fp8(b[0] * g[4], b[1] * g[5], b[2] * g[6], b[3] * g[7]);
;       *(u32x2*)(ao0 + ob + (unsigned)(i * 4) * DM) = w; }
	v_lshlrev_b32_e32 v5, 16, v48
	v_mul_f32_e32 v10, 0xbfb8aa3b, v5
	v_and_b32_e32 v6, 0xffff0000, v48
	v_exp_f32_e32 v10, v10
	v_mul_f32_e32 v11, 0xbfb8aa3b, v6
	v_exp_f32_e32 v11, v11
	v_lshlrev_b32_e32 v21, 16, v50
	v_add_f32_e32 v10, 1.0, v10
	v_rcp_f32_e32 v18, v10
	v_add_f32_e32 v10, 1.0, v11
	v_rcp_f32_e32 v19, v10
	v_mul_f32_e32 v22, 0xbfb8aa3b, v21
	v_mul_f32_e32 v5, v18, v5
	v_lshlrev_b32_e32 v18, 16, v49
	v_mul_f32_e32 v6, v19, v6
	v_mul_f32_e32 v19, 0xbfb8aa3b, v18
	v_and_b32_e32 v7, 0xffff0000, v49
	v_exp_f32_e32 v19, v19
	v_mul_f32_e32 v20, 0xbfb8aa3b, v7
	v_exp_f32_e32 v20, v20
	v_exp_f32_e32 v22, v22
	v_add_f32_e32 v19, 1.0, v19
	v_rcp_f32_e32 v19, v19
	v_add_f32_e32 v20, 1.0, v20
	v_rcp_f32_e32 v20, v20
	v_and_b32_e32 v8, 0xffff0000, v50
	v_mul_f32_e32 v18, v19, v18
	v_add_f32_e32 v19, 1.0, v22
	v_mul_f32_e32 v7, v20, v7
	v_rcp_f32_e32 v19, v19
	v_mul_f32_e32 v20, 0xbfb8aa3b, v8
	v_exp_f32_e32 v20, v20
	ds_read_b128 v[10:13], v4 offset:4096
	ds_read_b128 v[14:17], v4 offset:4112
	v_mul_f32_e32 v19, v19, v21
	v_lshlrev_b32_e32 v21, 16, v51
	v_and_b32_e32 v9, 0xffff0000, v51
	v_add_f32_e32 v20, 1.0, v20
	v_mul_f32_e32 v22, 0xbfb8aa3b, v21
	v_mul_f32_e32 v23, 0xbfb8aa3b, v9
	v_rcp_f32_e32 v20, v20
	v_exp_f32_e32 v22, v22
	v_exp_f32_e32 v23, v23
	v_mul_f32_e32 v5, 0x42800000, v5
	v_mul_f32_e32 v8, v20, v8
	v_add_f32_e32 v20, 1.0, v22
	v_add_f32_e32 v22, 1.0, v23
	v_mul_f32_e32 v6, 0x42800000, v6
	v_rcp_f32_e32 v20, v20
	v_rcp_f32_e32 v22, v22
	v_mul_f32_e32 v18, 0x42800000, v18
	v_mul_f32_e32 v7, 0x42800000, v7
	v_mul_f32_e32 v19, 0x42800000, v19
	v_mul_f32_e32 v8, 0x42800000, v8
	s_waitcnt lgkmcnt(1)
	v_mul_f32_e32 v5, v10, v5
	v_mul_f32_e32 v10, v11, v6
	v_mov_b32_e32 v6, v161
	v_mul_f32_e32 v11, v12, v18
	v_mul_f32_e32 v12, v13, v7
	v_cvt_pk_fp8_f32 v6, v5, v10
	s_waitcnt lgkmcnt(0)
	v_mul_f32_e32 v5, v14, v19
	v_mul_f32_e32 v8, v15, v8
	v_mov_b32_e32 v7, v161
	v_cvt_pk_fp8_f32 v7, v5, v8
	v_mul_f32_e32 v20, v20, v21
	v_mul_f32_e32 v9, v22, v9
	v_mul_f32_e32 v20, 0x42800000, v20
	v_mul_f32_e32 v9, 0x42800000, v9
	v_mul_f32_e32 v5, v16, v20
	v_mul_f32_e32 v8, v17, v9
	v_cvt_pk_fp8_f32 v6, v11, v12 op_sel:[0,0,1]
	v_cvt_pk_fp8_f32 v7, v5, v8 op_sel:[0,0,1]
	v_add_co_u32_e32 v8, vcc, s93, v0
	s_nop 1
	v_addc_co_u32_e32 v9, vcc, 0, v1, vcc
	global_store_dwordx2 v[8:9], v[6:7], off
	v_add_co_u32_e32 v6, vcc, s4, v2
	s_movk_i32 s4, 0x6000
	s_nop 0
	v_addc_co_u32_e32 v7, vcc, 0, v3, vcc
	ds_read_b128 v[10:13], v4 offset:6144
	ds_read_b128 v[14:17], v4 offset:6160
	s_waitcnt vmcnt(7)
	v_lshlrev_b32_e32 v5, 16, v52
	v_and_b32_e32 v6, 0xffff0000, v52
	v_mul_f32_e32 v19, 0xbfb8aa3b, v5
	v_mul_f32_e32 v20, 0xbfb8aa3b, v6
	v_exp_f32_e32 v19, v19
	v_exp_f32_e32 v20, v20
	v_lshlrev_b32_e32 v18, 16, v53
	v_and_b32_e32 v7, 0xffff0000, v53
	v_mul_f32_e32 v21, 0xbfb8aa3b, v18
	v_add_f32_e32 v19, 1.0, v19
	v_mul_f32_e32 v22, 0xbfb8aa3b, v7
	v_add_f32_e32 v20, 1.0, v20
	v_rcp_f32_e32 v19, v19
	v_exp_f32_e32 v21, v21
	v_rcp_f32_e32 v20, v20
	v_exp_f32_e32 v22, v22
	v_mul_f32_e32 v5, v19, v5
	v_add_f32_e32 v19, 1.0, v21
	v_lshlrev_b32_e32 v21, 16, v54
	v_mul_f32_e32 v6, v20, v6
	v_add_f32_e32 v20, 1.0, v22
	v_mul_f32_e32 v22, 0xbfb8aa3b, v21
	v_rcp_f32_e32 v19, v19
	v_exp_f32_e32 v22, v22
	v_rcp_f32_e32 v20, v20
	v_and_b32_e32 v8, 0xffff0000, v54
	v_mul_f32_e32 v18, v19, v18
	v_add_f32_e32 v19, 1.0, v22
	v_mul_f32_e32 v7, v20, v7
	v_rcp_f32_e32 v19, v19
	v_mul_f32_e32 v20, 0xbfb8aa3b, v8
	v_exp_f32_e32 v20, v20
	v_mul_f32_e32 v5, 0x42800000, v5
	v_mul_f32_e32 v19, v19, v21
	v_lshlrev_b32_e32 v21, 16, v55
	v_and_b32_e32 v9, 0xffff0000, v55
	v_add_f32_e32 v20, 1.0, v20
	v_mul_f32_e32 v22, 0xbfb8aa3b, v21
	v_mul_f32_e32 v23, 0xbfb8aa3b, v9
	v_rcp_f32_e32 v20, v20
	v_exp_f32_e32 v22, v22
	v_exp_f32_e32 v23, v23
	v_mul_f32_e32 v6, 0x42800000, v6
	v_mul_f32_e32 v8, v20, v8
	v_add_f32_e32 v20, 1.0, v22
	v_add_f32_e32 v22, 1.0, v23
	v_rcp_f32_e32 v20, v20
	v_rcp_f32_e32 v22, v22
	v_mul_f32_e32 v18, 0x42800000, v18
	v_mul_f32_e32 v7, 0x42800000, v7
	v_mul_f32_e32 v19, 0x42800000, v19
	v_mul_f32_e32 v8, 0x42800000, v8
	s_waitcnt lgkmcnt(1)
	v_mul_f32_e32 v5, v10, v5
	v_mul_f32_e32 v10, v11, v6
	v_mov_b32_e32 v6, v161
	v_mul_f32_e32 v11, v12, v18
	v_mul_f32_e32 v12, v13, v7
	v_cvt_pk_fp8_f32 v6, v5, v10
	s_waitcnt lgkmcnt(0)
	v_mul_f32_e32 v5, v14, v19
	v_mul_f32_e32 v8, v15, v8
	v_mov_b32_e32 v7, v161
	v_cvt_pk_fp8_f32 v7, v5, v8
	v_mul_f32_e32 v20, v20, v21
	v_mul_f32_e32 v9, v22, v9
	v_mul_f32_e32 v20, 0x42800000, v20
	v_mul_f32_e32 v9, 0x42800000, v9
	v_mul_f32_e32 v5, v16, v20
	v_mul_f32_e32 v8, v17, v9
	v_cvt_pk_fp8_f32 v6, v11, v12 op_sel:[0,0,1]
	v_cvt_pk_fp8_f32 v7, v5, v8 op_sel:[0,0,1]
	v_add_co_u32_e32 v8, vcc, s4, v0
	s_mov_b32 s4, 0x29000
	s_nop 0
	v_addc_co_u32_e32 v9, vcc, 0, v1, vcc
	global_store_dwordx2 v[8:9], v[6:7], off
	v_add_co_u32_e32 v6, vcc, s4, v2
	s_mov_b32 s4, 0x33000
	s_nop 0
	v_addc_co_u32_e32 v7, vcc, 0, v3, vcc
	ds_read_b128 v[10:13], v4 offset:8192
	ds_read_b128 v[14:17], v4 offset:8208
	s_waitcnt vmcnt(7)
; __device__ __forceinline__ unsigned pk4_fp8(float a, float b, float c, float d) { int p = __builtin_amdgcn_cvt_pk_fp8_f32(a, b, 0, false); return (unsigned)__builtin_amdgcn_cvt_pk_fp8_f32(c, d, p, true); }
; __device__ __forceinline__ float bf2f(bf16_t b) { return __uint_as_float((unsigned)b << 16); }
; __device__ __forceinline__ float silu_f(float z) { return z * __builtin_amdgcn_rcpf(1.f + __builtin_amdgcn_exp2f(-1.4426950408889634f * z)); }
;   __device__ __forceinline__ void operator()(f32x16 (&o)[4], const float (&rli)[16], int wid, int r32, int hi, int lane, char* lds) const {
;     ...
;     for (int i = 0; i < 8; ++i) {
;       const f32x4 a = *(const f32x4*)(st + sb + i * 512), b = *(const f32x4*)(st + sb + i * 512 + 4);
;       const bf16x8 zz = *(const bf16x8*)(z0 + zb + (unsigned)(i * 4) * A_IN);
;       float g[8];
; #pragma unroll
;       for (int k = 0; k < 8; ++k) g[k] = silu_f(bf2f((bf16_t)zz[k])) * F8_ASCALE;
;       u32x2 w; w.x = pk4_fp8(a[0] * g[0], a[1] * g[1], a[2] * g[2], a[3] * g[3]); w.y = pk4_fp8(b[0] * g[4], b[1] * g[5], b[2] * g[6], b[3] * g[7]);
;       *(u32x2*)(ao0 + ob + (unsigned)(i * 4) * DM) = w; }
	v_lshlrev_b32_e32 v5, 16, v56
	v_and_b32_e32 v6, 0xffff0000, v56
	v_lshlrev_b32_e32 v18, 16, v57
	v_mul_f32_e32 v20, 0xbfb8aa3b, v5
	v_mul_f32_e32 v21, 0xbfb8aa3b, v6
	v_mul_f32_e32 v22, 0xbfb8aa3b, v18
	v_exp_f32_e32 v20, v20
	v_exp_f32_e32 v21, v21
	v_exp_f32_e32 v22, v22
	v_and_b32_e32 v7, 0xffff0000, v57
	v_add_f32_e32 v20, 1.0, v20
	v_lshlrev_b32_e32 v19, 16, v58
	v_and_b32_e32 v8, 0xffff0000, v58
	v_add_f32_e32 v21, 1.0, v21
	v_add_f32_e32 v22, 1.0, v22
	v_rcp_f32_e32 v20, v20
	v_mul_f32_e32 v23, 0xbfb8aa3b, v7
	v_mul_f32_e32 v24, 0xbfb8aa3b, v19
	v_mul_f32_e32 v25, 0xbfb8aa3b, v8
	v_rcp_f32_e32 v21, v21
	v_rcp_f32_e32 v22, v22
	v_exp_f32_e32 v23, v23
	v_exp_f32_e32 v24, v24
	v_exp_f32_e32 v25, v25
	v_mul_f32_e32 v5, v20, v5
	v_lshlrev_b32_e32 v20, 16, v59
	v_and_b32_e32 v9, 0xffff0000, v59
	v_mul_f32_e32 v6, v21, v6
	v_mul_f32_e32 v18, v22, v18
	v_mul_f32_e32 v21, 0xbfb8aa3b, v20
	v_mul_f32_e32 v22, 0xbfb8aa3b, v9
	v_add_f32_e32 v23, 1.0, v23
	v_add_f32_e32 v24, 1.0, v24
	v_add_f32_e32 v25, 1.0, v25
	v_exp_f32_e32 v21, v21
	v_exp_f32_e32 v22, v22
	v_rcp_f32_e32 v23, v23
	v_rcp_f32_e32 v24, v24
	v_rcp_f32_e32 v25, v25
	v_add_f32_e32 v21, 1.0, v21
	v_add_f32_e32 v22, 1.0, v22
	v_mul_f32_e32 v7, v23, v7
	v_mul_f32_e32 v19, v24, v19
	v_mul_f32_e32 v5, 0x42800000, v5
	v_mul_f32_e32 v6, 0x42800000, v6
	v_mul_f32_e32 v8, v25, v8
	v_rcp_f32_e32 v21, v21
	v_rcp_f32_e32 v22, v22
	v_mul_f32_e32 v18, 0x42800000, v18
	v_mul_f32_e32 v7, 0x42800000, v7
	v_mul_f32_e32 v19, 0x42800000, v19
	v_mul_f32_e32 v8, 0x42800000, v8
	s_waitcnt lgkmcnt(1)
	v_mul_f32_e32 v5, v10, v5
	v_mul_f32_e32 v10, v11, v6
	v_mov_b32_e32 v6, v161
	v_mul_f32_e32 v11, v12, v18
	v_mul_f32_e32 v12, v13, v7
	v_cvt_pk_fp8_f32 v6, v5, v10
	s_waitcnt lgkmcnt(0)
	v_mul_f32_e32 v5, v14, v19
	v_mul_f32_e32 v8, v15, v8
	v_mov_b32_e32 v7, v161
	v_cvt_pk_fp8_f32 v7, v5, v8
	v_mul_f32_e32 v20, v21, v20
	v_mul_f32_e32 v9, v22, v9
	v_mul_f32_e32 v20, 0x42800000, v20
	v_mul_f32_e32 v9, 0x42800000, v9
	v_mul_f32_e32 v5, v16, v20
	v_mul_f32_e32 v8, v17, v9
	v_cvt_pk_fp8_f32 v6, v11, v12 op_sel:[0,0,1]
	v_cvt_pk_fp8_f32 v7, v5, v8 op_sel:[0,0,1]
	v_add_co_u32_e32 v8, vcc, s66, v0
	v_mov_b32_e32 v18, v161
	s_nop 0
	v_addc_co_u32_e32 v9, vcc, 0, v1, vcc
	global_store_dwordx2 v[8:9], v[6:7], off
	v_add_co_u32_e32 v6, vcc, s4, v2
	v_mov_b32_e32 v19, v161
	s_nop 0
	v_addc_co_u32_e32 v7, vcc, 0, v3, vcc
	ds_read_b128 v[10:13], v4 offset:10240
	ds_read_b128 v[14:17], v4 offset:10256
	s_mov_b32 s4, 0xa000
	s_waitcnt vmcnt(7)
	v_lshlrev_b32_e32 v5, 16, v60
	v_and_b32_e32 v6, 0xffff0000, v60
	v_lshlrev_b32_e32 v21, 16, v62
	v_and_b32_e32 v8, 0xffff0000, v62
	v_mul_f32_e32 v23, 0xbfb8aa3b, v5
	v_mul_f32_e32 v24, 0xbfb8aa3b, v6
	v_mul_f32_e32 v27, 0xbfb8aa3b, v21
	v_mul_f32_e32 v28, 0xbfb8aa3b, v8
	v_exp_f32_e32 v23, v23
	v_exp_f32_e32 v24, v24
	v_exp_f32_e32 v27, v27
	v_exp_f32_e32 v28, v28
	v_lshlrev_b32_e32 v20, 16, v61
	v_and_b32_e32 v7, 0xffff0000, v61
	v_lshlrev_b32_e32 v22, 16, v63
	v_and_b32_e32 v9, 0xffff0000, v63
	v_mul_f32_e32 v25, 0xbfb8aa3b, v20
	v_mul_f32_e32 v26, 0xbfb8aa3b, v7
	v_mul_f32_e32 v29, 0xbfb8aa3b, v22
	v_mul_f32_e32 v30, 0xbfb8aa3b, v9
	v_add_f32_e32 v23, 1.0, v23
	v_add_f32_e32 v24, 1.0, v24
	v_exp_f32_e32 v25, v25
	v_exp_f32_e32 v26, v26
	v_exp_f32_e32 v29, v29
	v_exp_f32_e32 v30, v30
	v_add_f32_e32 v27, 1.0, v27
	v_add_f32_e32 v28, 1.0, v28
	v_rcp_f32_e32 v23, v23
	v_rcp_f32_e32 v24, v24
	v_rcp_f32_e32 v27, v27
	v_rcp_f32_e32 v28, v28
	v_add_f32_e32 v25, 1.0, v25
	v_add_f32_e32 v26, 1.0, v26
	v_add_f32_e32 v29, 1.0, v29
	v_add_f32_e32 v30, 1.0, v30
	v_mul_f32_e32 v5, v23, v5
	v_mul_f32_e32 v6, v24, v6
	v_rcp_f32_e32 v25, v25
	v_rcp_f32_e32 v26, v26
	v_rcp_f32_e32 v29, v29
	v_rcp_f32_e32 v30, v30
	v_mul_f32_e32 v21, v27, v21
	v_mul_f32_e32 v8, v28, v8
	v_mul_f32_e32 v5, 0x42800000, v5
	v_mul_f32_e32 v6, 0x42800000, v6
	v_mul_f32_e32 v21, 0x42800000, v21
	v_mul_f32_e32 v8, 0x42800000, v8
	s_waitcnt lgkmcnt(1)
	v_mul_f32_e32 v5, v10, v5
	v_mul_f32_e32 v6, v11, v6
	v_cvt_pk_fp8_f32 v18, v5, v6
	s_waitcnt lgkmcnt(0)
	v_mul_f32_e32 v5, v14, v21
	v_mul_f32_e32 v6, v15, v8
	v_cvt_pk_fp8_f32 v19, v5, v6
	v_mul_f32_e32 v20, v25, v20
	v_mul_f32_e32 v7, v26, v7
	v_mul_f32_e32 v22, v29, v22
	v_mul_f32_e32 v9, v30, v9
	v_mul_f32_e32 v20, 0x42800000, v20
	v_mul_f32_e32 v7, 0x42800000, v7
	v_mul_f32_e32 v22, 0x42800000, v22
	v_mul_f32_e32 v9, 0x42800000, v9
	v_mul_f32_e32 v10, v12, v20
	v_mul_f32_e32 v7, v13, v7
	v_mul_f32_e32 v5, v16, v22
	v_mul_f32_e32 v6, v17, v9
	v_cvt_pk_fp8_f32 v18, v10, v7 op_sel:[0,0,1]
	v_cvt_pk_fp8_f32 v19, v5, v6 op_sel:[0,0,1]
	v_add_co_u32_e32 v6, vcc, s4, v0
	s_mov_b32 s4, 0x3d000
	s_nop 0
	v_addc_co_u32_e32 v7, vcc, 0, v1, vcc
	global_store_dwordx2 v[6:7], v[18:19], off
	v_add_co_u32_e32 v6, vcc, s4, v2
	v_mov_b32_e32 v18, v161
	s_nop 0
	v_addc_co_u32_e32 v7, vcc, 0, v3, vcc
	ds_read_b128 v[10:13], v4 offset:12288
	ds_read_b128 v[14:17], v4 offset:12304
	v_mov_b32_e32 v19, v161
	s_mov_b32 s4, 0x47000
	v_add_co_u32_e32 v2, vcc, s4, v2
	s_waitcnt vmcnt(7)
; __device__ __forceinline__ unsigned pk4_fp8(float a, float b, float c, float d) { int p = __builtin_amdgcn_cvt_pk_fp8_f32(a, b, 0, false); return (unsigned)__builtin_amdgcn_cvt_pk_fp8_f32(c, d, p, true); }
; __device__ __forceinline__ float bf2f(bf16_t b) { return __uint_as_float((unsigned)b << 16); }
; __device__ __forceinline__ float silu_f(float z) { return z * __builtin_amdgcn_rcpf(1.f + __builtin_amdgcn_exp2f(-1.4426950408889634f * z)); }
;   __device__ __forceinline__ void operator()(f32x16 (&o)[4], const float (&rli)[16], int wid, int r32, int hi, int lane, char* lds) const {
;     ...
;     for (int i = 0; i < 8; ++i) {
;       const f32x4 a = *(const f32x4*)(st + sb + i * 512), b = *(const f32x4*)(st + sb + i * 512 + 4);
;       const bf16x8 zz = *(const bf16x8*)(z0 + zb + (unsigned)(i * 4) * A_IN);
;       float g[8];
; #pragma unroll
;       for (int k = 0; k < 8; ++k) g[k] = silu_f(bf2f((bf16_t)zz[k])) * F8_ASCALE;
;       u32x2 w; w.x = pk4_fp8(a[0] * g[0], a[1] * g[1], a[2] * g[2], a[3] * g[3]); w.y = pk4_fp8(b[0] * g[4], b[1] * g[5], b[2] * g[6], b[3] * g[7]);
;       *(u32x2*)(ao0 + ob + (unsigned)(i * 4) * DM) = w; }
;     __syncthreads();
;   }
	v_lshlrev_b32_e32 v5, 16, v64
	v_and_b32_e32 v6, 0xffff0000, v64
	v_lshlrev_b32_e32 v21, 16, v66
	v_and_b32_e32 v8, 0xffff0000, v66
	v_mul_f32_e32 v23, 0xbfb8aa3b, v5
	v_mul_f32_e32 v24, 0xbfb8aa3b, v6
	v_mul_f32_e32 v27, 0xbfb8aa3b, v21
	v_mul_f32_e32 v28, 0xbfb8aa3b, v8
	v_exp_f32_e32 v23, v23
	v_exp_f32_e32 v24, v24
	v_exp_f32_e32 v27, v27
	v_exp_f32_e32 v28, v28
	v_lshlrev_b32_e32 v20, 16, v65
	v_and_b32_e32 v7, 0xffff0000, v65
	v_lshlrev_b32_e32 v22, 16, v67
	v_and_b32_e32 v9, 0xffff0000, v67
	v_mul_f32_e32 v25, 0xbfb8aa3b, v20
	v_mul_f32_e32 v26, 0xbfb8aa3b, v7
	v_mul_f32_e32 v29, 0xbfb8aa3b, v22
	v_mul_f32_e32 v30, 0xbfb8aa3b, v9
	v_exp_f32_e32 v25, v25
	v_exp_f32_e32 v26, v26
	v_exp_f32_e32 v29, v29
	v_exp_f32_e32 v30, v30
	v_add_f32_e32 v23, 1.0, v23
	v_add_f32_e32 v24, 1.0, v24
	v_add_f32_e32 v27, 1.0, v27
	v_add_f32_e32 v28, 1.0, v28
	v_rcp_f32_e32 v23, v23
	v_rcp_f32_e32 v24, v24
	v_rcp_f32_e32 v27, v27
	v_rcp_f32_e32 v28, v28
	v_add_f32_e32 v25, 1.0, v25
	v_add_f32_e32 v26, 1.0, v26
	v_add_f32_e32 v29, 1.0, v29
	v_add_f32_e32 v30, 1.0, v30
	v_rcp_f32_e32 v25, v25
	v_rcp_f32_e32 v26, v26
	v_rcp_f32_e32 v29, v29
	v_rcp_f32_e32 v30, v30
	v_mul_f32_e32 v5, v23, v5
	v_mul_f32_e32 v6, v24, v6
	v_mul_f32_e32 v21, v27, v21
	v_mul_f32_e32 v8, v28, v8
	v_mul_f32_e32 v5, 0x42800000, v5
	v_mul_f32_e32 v6, 0x42800000, v6
	v_mul_f32_e32 v21, 0x42800000, v21
	v_mul_f32_e32 v8, 0x42800000, v8
	s_waitcnt lgkmcnt(1)
	v_mul_f32_e32 v5, v10, v5
	v_mul_f32_e32 v6, v11, v6
	s_waitcnt lgkmcnt(0)
	v_mul_f32_e32 v11, v14, v21
	v_mul_f32_e32 v8, v15, v8
	v_cvt_pk_fp8_f32 v18, v5, v6
	v_cvt_pk_fp8_f32 v19, v11, v8
	v_mul_f32_e32 v20, v25, v20
	v_mul_f32_e32 v7, v26, v7
	v_mul_f32_e32 v22, v29, v22
	v_mul_f32_e32 v9, v30, v9
	v_mul_f32_e32 v20, 0x42800000, v20
	v_mul_f32_e32 v7, 0x42800000, v7
	v_mul_f32_e32 v22, 0x42800000, v22
	v_mul_f32_e32 v9, 0x42800000, v9
	v_mul_f32_e32 v10, v12, v20
	v_mul_f32_e32 v7, v13, v7
	v_mul_f32_e32 v5, v16, v22
	v_mul_f32_e32 v6, v17, v9
	v_cvt_pk_fp8_f32 v18, v10, v7 op_sel:[0,0,1]
	v_cvt_pk_fp8_f32 v19, v5, v6 op_sel:[0,0,1]
	v_addc_co_u32_e32 v3, vcc, 0, v3, vcc
	v_add_co_u32_e32 v6, vcc, s95, v0
	v_mov_b32_e32 v14, v161
	s_nop 0
	v_addc_co_u32_e32 v7, vcc, 0, v1, vcc
	global_store_dwordx2 v[6:7], v[18:19], off
	ds_read_b128 v[10:13], v4 offset:14336
	ds_read_b128 v[2:5], v4 offset:14352
	v_mov_b32_e32 v15, v161
	v_add_co_u32_e32 v0, vcc, 0xe000, v0
	s_waitcnt vmcnt(7)
	v_lshlrev_b32_e32 v16, 16, v68
	v_and_b32_e32 v6, 0xffff0000, v68
	v_lshlrev_b32_e32 v18, 16, v70
	v_and_b32_e32 v8, 0xffff0000, v70
	v_mul_f32_e32 v20, 0xbfb8aa3b, v16
	v_mul_f32_e32 v21, 0xbfb8aa3b, v6
	v_mul_f32_e32 v24, 0xbfb8aa3b, v18
	v_mul_f32_e32 v25, 0xbfb8aa3b, v8
	v_exp_f32_e32 v20, v20
	v_exp_f32_e32 v21, v21
	v_exp_f32_e32 v24, v24
	v_exp_f32_e32 v25, v25
	v_lshlrev_b32_e32 v17, 16, v69
	v_and_b32_e32 v7, 0xffff0000, v69
	v_lshlrev_b32_e32 v19, 16, v71
	v_and_b32_e32 v9, 0xffff0000, v71
	v_mul_f32_e32 v22, 0xbfb8aa3b, v17
	v_mul_f32_e32 v23, 0xbfb8aa3b, v7
	v_mul_f32_e32 v26, 0xbfb8aa3b, v19
	v_mul_f32_e32 v27, 0xbfb8aa3b, v9
	v_exp_f32_e32 v22, v22
	v_exp_f32_e32 v23, v23
	v_exp_f32_e32 v26, v26
	v_exp_f32_e32 v27, v27
	v_add_f32_e32 v20, 1.0, v20
	v_add_f32_e32 v21, 1.0, v21
	v_add_f32_e32 v24, 1.0, v24
	v_add_f32_e32 v25, 1.0, v25
	v_rcp_f32_e32 v20, v20
	v_rcp_f32_e32 v21, v21
	v_rcp_f32_e32 v24, v24
	v_rcp_f32_e32 v25, v25
	v_add_f32_e32 v22, 1.0, v22
	v_add_f32_e32 v23, 1.0, v23
	v_add_f32_e32 v26, 1.0, v26
	v_add_f32_e32 v27, 1.0, v27
	v_rcp_f32_e32 v22, v22
	v_rcp_f32_e32 v23, v23
	v_rcp_f32_e32 v26, v26
	v_rcp_f32_e32 v27, v27
	v_mul_f32_e32 v16, v20, v16
	v_mul_f32_e32 v6, v21, v6
	v_mul_f32_e32 v18, v24, v18
	v_mul_f32_e32 v8, v25, v8
	v_mul_f32_e32 v16, 0x42800000, v16
	v_mul_f32_e32 v6, 0x42800000, v6
	v_mul_f32_e32 v18, 0x42800000, v18
	v_mul_f32_e32 v8, 0x42800000, v8
	s_waitcnt lgkmcnt(1)
	v_mul_f32_e32 v10, v10, v16
	v_mul_f32_e32 v6, v11, v6
	s_waitcnt lgkmcnt(0)
	v_mul_f32_e32 v2, v2, v18
	v_mul_f32_e32 v3, v3, v8
	v_cvt_pk_fp8_f32 v14, v10, v6
	v_cvt_pk_fp8_f32 v15, v2, v3
	v_mul_f32_e32 v17, v22, v17
	v_mul_f32_e32 v7, v23, v7
	v_mul_f32_e32 v19, v26, v19
	v_mul_f32_e32 v9, v27, v9
	v_mul_f32_e32 v17, 0x42800000, v17
	v_mul_f32_e32 v7, 0x42800000, v7
	v_mul_f32_e32 v19, 0x42800000, v19
	v_mul_f32_e32 v9, 0x42800000, v9
	v_mul_f32_e32 v11, v12, v17
	v_mul_f32_e32 v7, v13, v7
	v_mul_f32_e32 v2, v4, v19
	v_mul_f32_e32 v3, v5, v9
	v_cvt_pk_fp8_f32 v14, v11, v7 op_sel:[0,0,1]
	v_cvt_pk_fp8_f32 v15, v2, v3 op_sel:[0,0,1]
	v_addc_co_u32_e32 v1, vcc, 0, v1, vcc
	global_store_dwordx2 v[0:1], v[14:15], off
	s_barrier
	s_cbranch_scc1 .LBB0_35
